# FFN2-in SwiGLU epilogue: the 8 per-row-block rstd chains batched up front (8 loads in flight, batched bpermutes), as done for the input projection
# speedup vs baseline: 1.0170x; 1.0170x over previous
; template <class Epi, class Sched, bool ALIGN_EPI = false, bool SP2 = false>
; __device__ __forceinline__ void gemm_phase(PG8_LAS unsigned char* lds, const Gemm g, const Sched& S, const Epi& E, const int tid_arg) {
;     ...
; #pragma unroll
;         for (int a = 0; a < 2; ++a)
; #pragma unroll
;             for (int b = 0; b < 2; ++b)
; #pragma unroll
;                 for (int m = 0; m < 4; ++m)
; #pragma unroll
;                     for (int n = 0; n < 2; ++n) acc[a][b][m][n] = (f32x4){0.f, 0.f, 0.f, 0.f};
;         cur = nxt; cA = nA; cB = nB; ++ui;
.LBB0_1169:
	s_add_u32 s23, s26, 0x100
	v_mov_b32_e32 v0, 0
	s_addc_u32 s46, s27, 0
	s_mov_b32 s47, -2
	v_mov_b32_e32 v1, v0
	v_mov_b32_e32 v2, v0
	v_mov_b32_e32 v3, v0
	v_mov_b32_e32 v4, v0
	v_mov_b32_e32 v5, v0
	v_mov_b32_e32 v6, v0
	v_mov_b32_e32 v7, v0
	v_mov_b32_e32 v16, v0
	v_mov_b32_e32 v17, v0
	v_mov_b32_e32 v18, v0
	v_mov_b32_e32 v19, v0
	v_mov_b32_e32 v20, v0
	v_mov_b32_e32 v21, v0
	v_mov_b32_e32 v22, v0
	v_mov_b32_e32 v23, v0
	v_mov_b32_e32 v32, v0
	v_mov_b32_e32 v33, v0
	v_mov_b32_e32 v34, v0
	v_mov_b32_e32 v35, v0
	v_mov_b32_e32 v36, v0
	v_mov_b32_e32 v37, v0
	v_mov_b32_e32 v38, v0
	v_mov_b32_e32 v39, v0
	v_mov_b32_e32 v48, v0
	v_mov_b32_e32 v49, v0
	v_mov_b32_e32 v50, v0
	v_mov_b32_e32 v51, v0
	v_mov_b32_e32 v52, v0
	v_mov_b32_e32 v53, v0
	v_mov_b32_e32 v54, v0
	v_mov_b32_e32 v55, v0
	v_mov_b32_e32 v8, v0
	v_mov_b32_e32 v9, v0
	v_mov_b32_e32 v10, v0
	v_mov_b32_e32 v11, v0
	v_mov_b32_e32 v12, v0
	v_mov_b32_e32 v13, v0
	v_mov_b32_e32 v14, v0
	v_mov_b32_e32 v15, v0
	v_mov_b32_e32 v24, v0
	v_mov_b32_e32 v25, v0
	v_mov_b32_e32 v26, v0
	v_mov_b32_e32 v27, v0
	v_mov_b32_e32 v28, v0
	v_mov_b32_e32 v29, v0
	v_mov_b32_e32 v30, v0
	v_mov_b32_e32 v31, v0
	v_mov_b32_e32 v40, v0
	v_mov_b32_e32 v41, v0
	v_mov_b32_e32 v42, v0
	v_mov_b32_e32 v43, v0
	v_mov_b32_e32 v44, v0
	v_mov_b32_e32 v45, v0
	v_mov_b32_e32 v46, v0
	v_mov_b32_e32 v47, v0
	v_mov_b32_e32 v56, v0
	v_mov_b32_e32 v57, v0
	v_mov_b32_e32 v58, v0
	v_mov_b32_e32 v59, v0
	v_mov_b32_e32 v60, v0
	v_mov_b32_e32 v61, v0
	v_mov_b32_e32 v62, v0
	v_mov_b32_e32 v63, v0
	v_mov_b32_e32 v64, v0
	v_mov_b32_e32 v65, v0
	v_mov_b32_e32 v66, v0
	v_mov_b32_e32 v67, v0
	v_mov_b32_e32 v68, v0
	v_mov_b32_e32 v69, v0
	v_mov_b32_e32 v70, v0
	v_mov_b32_e32 v71, v0
	v_mov_b32_e32 v80, v0
	v_mov_b32_e32 v81, v0
	v_mov_b32_e32 v82, v0
	v_mov_b32_e32 v83, v0
	v_mov_b32_e32 v84, v0
	v_mov_b32_e32 v85, v0
	v_mov_b32_e32 v86, v0
	v_mov_b32_e32 v87, v0
	v_mov_b32_e32 v96, v0
	v_mov_b32_e32 v97, v0
	v_mov_b32_e32 v98, v0
	v_mov_b32_e32 v99, v0
	v_mov_b32_e32 v100, v0
	v_mov_b32_e32 v101, v0
	v_mov_b32_e32 v102, v0
	v_mov_b32_e32 v103, v0
	v_mov_b32_e32 v112, v0
	v_mov_b32_e32 v113, v0
	v_mov_b32_e32 v114, v0
	v_mov_b32_e32 v115, v0
	v_mov_b32_e32 v116, v0
	v_mov_b32_e32 v117, v0
	v_mov_b32_e32 v118, v0
	v_mov_b32_e32 v119, v0
	v_mov_b32_e32 v72, v0
	v_mov_b32_e32 v73, v0
	v_mov_b32_e32 v74, v0
	v_mov_b32_e32 v75, v0
	v_mov_b32_e32 v76, v0
	v_mov_b32_e32 v77, v0
	v_mov_b32_e32 v78, v0
	v_mov_b32_e32 v79, v0
	v_mov_b32_e32 v88, v0
	v_mov_b32_e32 v89, v0
	v_mov_b32_e32 v90, v0
	v_mov_b32_e32 v91, v0
	v_mov_b32_e32 v92, v0
	v_mov_b32_e32 v93, v0
	v_mov_b32_e32 v94, v0
	v_mov_b32_e32 v95, v0
	v_mov_b32_e32 v104, v0
	v_mov_b32_e32 v105, v0
	v_mov_b32_e32 v106, v0
	v_mov_b32_e32 v107, v0
	v_mov_b32_e32 v108, v0
	v_mov_b32_e32 v109, v0
	v_mov_b32_e32 v110, v0
	v_mov_b32_e32 v111, v0
	v_mov_b32_e32 v120, v0
	v_mov_b32_e32 v121, v0
	v_mov_b32_e32 v122, v0
	v_mov_b32_e32 v123, v0
	v_mov_b32_e32 v124, v0
	v_mov_b32_e32 v125, v0
	v_mov_b32_e32 v126, v0
	v_mov_b32_e32 v127, v0
	s_nop 0
	s_nop 0
	s_nop 0
	s_nop 0
	s_nop 0
	s_nop 0
	s_nop 0
	s_nop 0
	s_nop 0
	s_nop 0
